# layer-1 SSM tables built by blocks 128-159 in their phase-7 (merge) slack instead of on the phase-8 critical path; plus NA item permutation
# speedup vs baseline: 1.0224x; 1.0194x over previous
.LBB0_8:
	v_writelane_b32 v255, 0, 62
	s_add_u32 s0, s0, 0x120
	s_addc_u32 s1, s1, 0
	v_writelane_b32 v253, s0, 4
	v_lshrrev_b32_e32 v1, 20, v0
	v_lshrrev_b32_e32 v0, 10, v0
	v_writelane_b32 v253, s1, 5
	s_and_b32 s0, s52, 7
	v_writelane_b32 v253, s0, 6
	s_lshr_b32 s0, s52, 3
	v_writelane_b32 v253, s0, 7
	s_lshl_b32 s0, s52, 3
	s_cmpk_lt_i32 s52, 0x510
	v_writelane_b32 v253, s0, 8
	s_cselect_b64 s[0:1], -1, 0
	v_writelane_b32 v253, s0, 9
	s_cmp_gt_i32 s52, 31
	v_or_b32_e32 v0, v0, v1
	v_writelane_b32 v253, s1, 10
	s_cselect_b64 s[0:1], -1, 0
	v_writelane_b32 v253, s0, 11
	s_cmpk_lt_u32 s52, 0x510
	s_mov_b32 s54, s52
	v_writelane_b32 v253, s1, 12
	s_cselect_b64 s[0:1], -1, 0
	v_writelane_b32 v253, s0, 13
	s_ashr_i32 s53, s52, 31
	s_lshl_b64 s[6:7], s[52:53], 18
	v_writelane_b32 v253, s1, 14
	s_sub_i32 s0, s52, 32
	v_writelane_b32 v253, s0, 15
	v_writelane_b32 v253, s6, 16
	s_lshl_b32 s0, s52, 6
	v_mbcnt_lo_u32_b32 v2, -1, 0
	v_writelane_b32 v253, s7, 17
	s_lshl_b64 s[6:7], s[52:53], 17
	v_writelane_b32 v253, s6, 18
	s_mov_b32 s53, s0
	s_lshl_b32 s0, s52, 9
	v_writelane_b32 v253, s7, 19
	v_writelane_b32 v253, s0, 20
	s_add_u32 s0, s2, 0x11a48200
	s_addc_u32 s1, s3, 0
	v_writelane_b32 v253, s0, 21
	v_mbcnt_hi_u32_b32 v172, -1, v2
	v_and_b32_e32 v2, 64, v172
	v_writelane_b32 v253, s1, 22
	s_add_u32 s0, s2, 0x11a48400
	s_addc_u32 s1, s3, 0
	v_writelane_b32 v253, s0, 23
	v_mov_b32_e32 v1, 0
	v_mov_b32_e32 v167, 0x358637bd
	v_writelane_b32 v253, s1, 24
	s_add_u32 s0, s2, 0x11a48500
	s_addc_u32 s1, s3, 0
	v_writelane_b32 v253, s0, 25
	v_mov_b32_e32 v168, 0x3c0881c4
	v_mov_b32_e32 v169, 0xbab64f3b
	v_writelane_b32 v253, s1, 26
	s_add_u32 s0, s2, 0x11a48600
	s_addc_u32 s1, s3, 0
	v_writelane_b32 v253, s0, 27
	v_mov_b32_e32 v170, 0x3ca908c9
	v_mov_b32_e32 v171, 1
	v_writelane_b32 v253, s1, 28
	s_add_u32 s0, s2, 0x11a48700
	s_addc_u32 s1, s3, 0
	v_writelane_b32 v253, s0, 29
	v_add_u32_e32 v173, 64, v2
	v_xor_b32_e32 v174, 32, v172
	v_writelane_b32 v253, s1, 30
	s_add_u32 s0, s2, 0x11a48800
	s_addc_u32 s1, s3, 0
	v_writelane_b32 v253, s0, 31
	v_xor_b32_e32 v175, 16, v172
	v_xor_b32_e32 v193, 2, v172
	v_writelane_b32 v253, s1, 32
	s_add_u32 s0, s2, 0x11a48900
	s_addc_u32 s1, s3, 0
	v_writelane_b32 v253, s0, 33
	v_xor_b32_e32 v252, 1, v172
	v_mov_b32_e32 v180, 0xbe48000
	v_writelane_b32 v253, s1, 34
	s_add_u32 s0, s2, 0x11a48a00
	s_addc_u32 s1, s3, 0
	v_writelane_b32 v253, s0, 35
	v_mov_b32_e32 v181, 0xab48000
	v_mov_b32_e32 v182, 0xd848000
	v_writelane_b32 v253, s1, 36
	s_add_u32 s0, s2, 0x11a48b00
	s_addc_u32 s1, s3, 0
	v_writelane_b32 v253, s0, 37
	v_mov_b32_e32 v183, 0xb1c8000
	v_mov_b32_e32 v184, 0x2c00
	v_writelane_b32 v253, s1, 38
	s_add_u32 s0, s2, 0x11a48c00
	s_addc_u32 s1, s3, 0
	v_writelane_b32 v253, s0, 39
	v_mov_b32_e32 v185, 0x20be0
	v_mov_b32_e32 v186, 0x7f800000
	v_writelane_b32 v253, s1, 40
	s_add_u32 s0, s2, 0x11a48d00
	s_addc_u32 s1, s3, 0
	v_writelane_b32 v253, s0, 41
	v_not_b32_e32 v187, 63
	v_not_b32_e32 v188, 31
	v_writelane_b32 v253, s1, 42
	s_add_u32 s0, s2, 0x11a48e00
	s_addc_u32 s1, s3, 0
	v_writelane_b32 v253, s0, 43
	v_mov_b32_e32 v189, 0x7fc00000
	v_mov_b32_e32 v190, 0xffffff00
	v_writelane_b32 v253, s1, 44
	s_add_u32 s0, s2, 0x11a48f00
	s_addc_u32 s1, s3, 0
	v_writelane_b32 v253, s0, 45
	v_mov_b32_e32 v191, 0xfffffe80
	v_mov_b32_e32 v192, 3
	v_writelane_b32 v253, s1, 46
	s_add_u32 s0, s2, 0x11a49000
	s_addc_u32 s1, s3, 0
	v_writelane_b32 v253, s0, 47
	v_mov_b32_e32 v156, 0xf149f2ca
	s_movk_i32 s33, 0x6000
	v_writelane_b32 v253, s1, 48
	s_add_u32 s0, s2, 0x11a49100
	s_addc_u32 s1, s3, 0
	v_writelane_b32 v253, s0, 49
	s_movk_i32 s83, 0x2000
	s_movk_i32 s86, 0x1fff
	v_writelane_b32 v253, s1, 50
	s_add_u32 s0, s2, 0x11a49200
	s_addc_u32 s1, s3, 0
	v_writelane_b32 v253, s0, 51
	s_movk_i32 s77, 0x1000
	s_mov_b32 s70, 0x800000
	v_writelane_b32 v253, s1, 52
	s_add_u32 s0, s2, 0x11a49300
	s_addc_u32 s1, s3, 0
	v_writelane_b32 v253, s0, 53
	s_cmp_eq_u32 s10, 15
	s_movk_i32 s96, 0x5000
	v_writelane_b32 v253, s1, 54
	s_cselect_b64 s[0:1], -1, 0
	v_writelane_b32 v253, s0, 55
	s_cmp_eq_u32 s10, 14
	s_mov_b32 s50, 0x8000
	v_writelane_b32 v253, s1, 56
	s_cselect_b64 s[0:1], -1, 0
	v_writelane_b32 v253, s0, 57
	s_cmp_eq_u32 s10, 13
	s_movk_i32 s55, 0xff
	v_writelane_b32 v253, s1, 58
	s_cselect_b64 s[0:1], -1, 0
	v_writelane_b32 v253, s0, 59
	s_cmp_eq_u32 s10, 12
	s_mov_b32 s51, 0x40000
	v_writelane_b32 v253, s1, 60
	s_cselect_b64 s[0:1], -1, 0
	v_writelane_b32 v253, s0, 61
	s_cmp_eq_u32 s10, 11
	s_movk_i32 s48, 0x1200
	v_writelane_b32 v253, s1, 62
	s_cselect_b64 s[0:1], -1, 0
	v_writelane_b32 v253, s0, 63
	s_cmp_eq_u32 s10, 10
	s_movk_i32 s31, 0x7fff
	v_writelane_b32 v254, s1, 0
	s_cselect_b64 s[0:1], -1, 0
	v_writelane_b32 v254, s0, 1
	s_cmp_eq_u32 s10, 9
	s_movk_i32 s49, 0x3000
	v_writelane_b32 v254, s1, 2
	s_cselect_b64 s[0:1], -1, 0
	v_writelane_b32 v254, s0, 3
	s_cmp_eq_u32 s10, 8
	s_movk_i32 s56, 0x4000
	v_writelane_b32 v254, s1, 4
	s_cselect_b64 s[0:1], -1, 0
	v_writelane_b32 v254, s0, 5
	s_cmp_eq_u32 s10, 7
	s_mov_b32 s57, 0x27fff
	v_writelane_b32 v254, s1, 6
	s_cselect_b64 s[0:1], -1, 0
	v_writelane_b32 v254, s0, 7
	s_cmp_eq_u32 s10, 6
	s_movk_i32 s65, 0x400
	v_writelane_b32 v254, s1, 8
	s_cselect_b64 s[0:1], -1, 0
	v_writelane_b32 v254, s0, 9
	s_cmp_eq_u32 s10, 5
	s_mov_b32 s97, 0x12000
	v_writelane_b32 v254, s1, 10
	s_cselect_b64 s[0:1], -1, 0
	v_writelane_b32 v254, s0, 11
	s_cmp_eq_u32 s10, 4
	s_mov_b32 s87, 0xc000
	v_writelane_b32 v254, s1, 12
	s_cselect_b64 s[0:1], -1, 0
	v_writelane_b32 v254, s0, 13
	s_cmp_eq_u32 s10, 3
	s_movk_i32 s75, 0x404
	v_writelane_b32 v254, s1, 14
	s_cselect_b64 s[0:1], -1, 0
	v_writelane_b32 v254, s0, 15
	s_cmp_eq_u32 s10, 2
	s_mov_b32 s71, 0xc2ce8ed0
	v_writelane_b32 v254, s1, 16
	s_cselect_b64 s[0:1], -1, 0
	v_writelane_b32 v254, s0, 17
	s_cmp_eq_u32 s10, 1
	s_mov_b32 s30, 0x42b17218
	v_writelane_b32 v254, s1, 18
	s_cselect_b64 s[0:1], -1, 0
	v_writelane_b32 v254, s0, 19
	s_cmp_eq_u32 s10, 0
	s_mov_b32 s21, 0x437f0000
	v_writelane_b32 v254, s1, 20
	s_cselect_b64 s[0:1], -1, 0
	v_writelane_b32 v254, s0, 21
	s_mov_b32 s35, 0x3e38aa3b
	s_movk_i32 s58, 0x21ff
	v_writelane_b32 v254, s1, 22
	s_lshl_b32 s0, s10, 8
	s_add_u32 s0, s4, s0
	s_addc_u32 s1, s5, 0
	s_add_u32 s4, s0, 0x1400
	s_addc_u32 s5, s1, 0
	v_writelane_b32 v254, s4, 23
	s_add_u32 s0, s0, 0x2400
	s_addc_u32 s1, s1, 0
	v_writelane_b32 v254, s5, 24
	v_writelane_b32 v254, s0, 25
	s_mov_b32 s29, 0
	s_mov_b64 s[84:85], 0x800
	v_writelane_b32 v254, s1, 26
	s_add_u32 s0, s2, 0x11a4b400
	s_addc_u32 s1, s3, 0
	v_writelane_b32 v254, s0, 27
	s_mov_b64 s[24:25], 0x80
	s_mov_b32 s76, 0x3fb8aa3b
	v_writelane_b32 v254, s1, 28
	s_add_u32 s0, s2, 0x11a4b500
	s_addc_u32 s1, s3, 0
	v_writelane_b32 v254, s0, 29
	s_mov_b64 s[78:79], 0x1ff80
	s_mov_b32 s64, 0x3f803f80
	v_writelane_b32 v254, s1, 30
	s_movk_i32 s0, 0x3ff
	v_and_or_b32 v0, v0, s0, v166
	s_add_i32 s0, 0, 0x4400
	v_writelane_b32 v254, s0, 31
	s_add_i32 s0, 0, 0x6400
	v_writelane_b32 v254, s0, 32
	s_add_i32 s0, 0, 0xa400
	v_writelane_b32 v254, s0, 33
	s_add_i32 s0, 0, 0x11800
	v_writelane_b32 v254, s0, 34
	s_add_i32 s0, 0, 0x11000
	v_writelane_b32 v254, s0, 35
	s_add_i32 s0, 0, 0x21140
	v_writelane_b32 v254, s0, 36
	s_add_i32 s0, 0, 0x21144
	v_writelane_b32 v254, s0, 37
	v_readlane_b32 s0, v253, 2
	v_readlane_b32 s1, v253, 3
	s_nop 0
	v_writelane_b32 v254, s0, 38
	v_cmp_eq_u32_e64 s[0:1], 0, v0
	s_nop 1
	v_writelane_b32 v254, s0, 39
	s_nop 1
	v_writelane_b32 v254, s1, 40
	v_writelane_b32 v254, s53, 41
	v_writelane_b32 v254, s52, 42
	s_nop 1
	v_writelane_b32 v254, s53, 43
	v_writelane_b32 v254, s54, 44
	s_branch .LBB0_13

.LBB0_176:
	v_readlane_b32 s0, v255, 62
	s_cmp_eq_u32 s0, 2
	s_cbranch_scc1 .LBB0_322
	s_andn2_b64 vcc, exec, s[48:49]
	s_cbranch_vccnz .LBB0_322
	v_readlane_b32 s0, v255, 55
	v_readlane_b32 s1, v255, 56
	s_andn2_b64 vcc, exec, s[0:1]
	s_mov_b64 s[0:1], -1
	s_cbranch_vccnz .LBB0_248
	v_readlane_b32 s52, v255, 22
	v_readlane_b32 s53, v255, 23
	s_branch .LBB0_180

.LBB0_1002:
	s_add_i32 s6, s6, s89
	s_add_i32 s10, s6, 0xfffffec0
	s_lshl_b32 s12, s10, 2
	s_add_i32 s11, s11, s13
	s_cmpk_gt_i32 s6, 0x33f
	s_cbranch_scc1 .LBB0_1243
.LBB0_1003:
	s_cmpk_gt_i32 s6, 0x13f
	s_mov_b64 s[0:1], -1
	s_cbranch_scc0 .LBB0_1204
	s_add_i32 s16, s6, 0xfffffec0
	s_cmpk_lg_i32 s89, 0x100
	s_cbranch_scc1 .Lna_nomap
	v_readlane_b32 s4, v255, 22
	s_cmpk_lt_i32 s4, 0x40
	s_cbranch_scc0 .Lna_hi
	s_lshl_b32 s16, s4, 3
	s_cmpk_lt_i32 s6, 0x300
	s_cbranch_scc1 .Lna_set
	s_add_i32 s16, s16, 7
	s_branch .Lna_set
.Lna_hi:
	s_sub_i32 s4, s4, 64
	s_lshl_b32 s4, s4, 1
	s_cmpk_lt_i32 s6, 0x200
	s_cbranch_scc1 .Lna_e
	s_add_i32 s4, s4, 1
.Lna_e:
	s_mul_hi_u32 s5, s4, 0xaaaaaaab
	s_lshr_b32 s5, s5, 2
	s_mul_i32 s0, s5, 6
	s_sub_i32 s0, s4, s0
	s_add_i32 s0, s0, 1
	s_lshl_b32 s16, s5, 3
	s_add_i32 s16, s16, s0
.Lna_set:
	s_mov_b32 s10, s16
	s_lshl_b32 s12, s16, 2
.Lna_nomap:
	v_mov_b32_e32 v0, v166
	v_mov_b32_e32 v6, v166
	v_mov_b32_e32 v2, v166
	s_movk_i32 s0, 0x1d1
	s_lshr_b32 s4, s16, 3
	s_bfe_u32 s5, s16, 0x30003
	s_waitcnt vmcnt(0)
	s_barrier
	s_nop 0
	v_cmp_gt_i32_e32 vcc, s0, v2
	s_and_saveexec_b64 s[0:1], vcc
	s_cbranch_execz .LBB0_1012
	v_max_i32_e32 v3, 0xffffffd1, v2
	v_sub_u32_e32 v3, v3, v2
	v_add_u32_e32 v3, 0x1ff, v3
	s_movk_i32 s2, 0x1ff
	v_cmp_lt_u32_e32 vcc, s2, v3
	s_mov_b64 s[8:9], -1
	s_and_saveexec_b64 s[2:3], vcc
	s_cbranch_execz .LBB0_1009
	v_readlane_b32 s7, v255, 34
	s_or_b32 s7, s5, s7
	s_mul_hi_i32 s9, s7, 0x744
	s_mulk_i32 s7, 0x744
	v_readlane_b32 s8, v255, 1
	v_lshrrev_b32_e32 v3, 9, v3
	s_add_u32 s8, s8, s7
	v_readlane_b32 s7, v255, 2
	v_add_u32_e32 v7, 1, v3
	s_addc_u32 s9, s7, s9
	v_and_b32_e32 v8, 0xfffffe, v7
	v_add_u32_e32 v3, 0x200, v2
	v_readlane_b32 s7, v254, 34
	s_mov_b64 s[18:19], 0
	v_mov_b32_e32 v10, v8
	v_lshl_add_u32 v9, v2, 2, s7
	v_mov_b64_e32 v[4:5], v[2:3]

.LBB0_1914:
	v_readlane_b32 s2, v254, 38
	v_readlane_b32 s0, v253, 2
	s_add_i32 s16, s2, 1
	s_cmpk_lg_i32 s89, 0x100
	s_cbranch_scc1 .Let_done
	s_cmp_eq_u32 s2, 7
	s_cbranch_scc0 .Let_not7
	v_readlane_b32 s3, v255, 22
	s_cmpk_lt_i32 s3, 0x80
	s_cbranch_scc1 .Let_done
	s_cmpk_lt_i32 s3, 0xa0
	s_cbranch_scc0 .Let_done
	s_mov_b32 s3, 1
	s_nop 0
	v_writelane_b32 v255, s3, 62
	s_mov_b32 s16, 8
	s_mov_b64 s[0:1], 0
	s_branch .LBB0_1969
.Let_not7:
	s_cmp_eq_u32 s2, 8
	s_cbranch_scc0 .Let_done
	v_readlane_b32 s3, v255, 62
	s_cmp_eq_u32 s3, 1
	s_cbranch_scc0 .Let_done
	s_mov_b32 s3, 2
	s_nop 0
	v_writelane_b32 v255, s3, 62
	s_mov_b32 s16, 8
.Let_done:
	v_readlane_b32 s1, v253, 3
	s_cmp_ge_i32 s16, s1
	s_mov_b64 s[0:1], -1
	s_cbranch_scc0 .LBB0_1915
	s_getpc_b64 s[98:99]
